# swiglu SS-load hoist + diff-attn 2-tile interleaved fast path + batched bias-table reduction
# speedup vs baseline: 1.0159x; 1.0049x over previous
; __global__ void __launch_bounds__(512, 2) fwd_megakernel(Params p) {
;     ...
;         for (int r = gw; r < 5632 + 3072 + 5632; r += ngw) {
;             const bf16_t* wrow; const float* sh; float* dst; int ncol;
;             if (r < 5632) { wrow = WGU0 + (size_t)r * 1024; sh = mod0 + 3072; dst = BT + BT_GU0 + r; ncol = 5632; }
;             else if (r < 5632 + 3072) { wrow = WQKV + (size_t)(r - 5632) * 1024; sh = mod1; dst = BT + BT_QKV + (r - 5632); ncol = 3072; }
;             else { wrow = WGU1 + (size_t)(r - 5632 - 3072) * 1024; sh = mod1 + 3072; dst = BT + BT_GU1 + (r - 5632 - 3072); ncol = 5632; }
;             const u32x4 w0 = *(const u32x4*)(wrow + 16 * lane), w1 = *(const u32x4*)(wrow + 16 * lane + 8);
;             const float wf[16] = {bflo(w0.x), bfhi(w0.x), bflo(w0.y), bfhi(w0.y), bflo(w0.z), bfhi(w0.z), bflo(w0.w), bfhi(w0.w), bflo(w1.x), bfhi(w1.x), bflo(w1.y), bfhi(w1.y), bflo(w1.z), bfhi(w1.z), bflo(w1.w), bfhi(w1.w)};
; #pragma unroll
;             for (int b = 0; b < 8; ++b) { const f32x4* sp = (const f32x4*)(sh + b * 6144 + 16 * lane); float a = 0.f;
; #pragma unroll
;                 for (int j = 0; j < 4; ++j) { const f32x4 sv = sp[j]; a += sv[0] * wf[4 * j] + sv[1] * wf[4 * j + 1] + sv[2] * wf[4 * j + 2] + sv[3] * wf[4 * j + 3]; }
;                 a = wave_sum(a); if (lane == 0) dst[(size_t)b * ncol] = a; }
.LBB0_186:
	global_load_dwordx4 v[12:15], v10, s[62:63]
	global_load_dwordx4 v[16:19], v10, s[62:63] offset:16
	s_mov_b64 s[76:77], s[60:61]
	global_load_dwordx4 v[70:73], v0, s[76:77]
	global_load_dwordx4 v[74:77], v0, s[76:77] offset:16
	global_load_dwordx4 v[78:81], v0, s[76:77] offset:32
	global_load_dwordx4 v[82:85], v0, s[76:77] offset:48
	s_add_u32 s76, s76, 0x6000
	s_addc_u32 s77, s77, 0
	global_load_dwordx4 v[86:89], v0, s[76:77]
	global_load_dwordx4 v[90:93], v0, s[76:77] offset:16
	global_load_dwordx4 v[94:97], v0, s[76:77] offset:32
	global_load_dwordx4 v[98:101], v0, s[76:77] offset:48
	s_add_u32 s76, s76, 0x6000
	s_addc_u32 s77, s77, 0
	global_load_dwordx4 v[114:117], v0, s[76:77]
	global_load_dwordx4 v[118:121], v0, s[76:77] offset:16
	global_load_dwordx4 v[122:125], v0, s[76:77] offset:32
	global_load_dwordx4 v[126:129], v0, s[76:77] offset:48
	s_add_u32 s76, s76, 0x6000
	s_addc_u32 s77, s77, 0
	global_load_dwordx4 v[180:183], v0, s[76:77]
	global_load_dwordx4 v[184:187], v0, s[76:77] offset:16
	global_load_dwordx4 v[188:191], v0, s[76:77] offset:32
	global_load_dwordx4 v[192:195], v0, s[76:77] offset:48
	s_add_u32 s76, s76, 0x6000
	s_addc_u32 s77, s77, 0
	global_load_dwordx4 v[200:203], v0, s[76:77]
	global_load_dwordx4 v[206:209], v0, s[76:77] offset:16
	global_load_dwordx4 v[210:213], v0, s[76:77] offset:32
	global_load_dwordx4 v[214:217], v0, s[76:77] offset:48
	s_add_u32 s76, s76, 0x6000
	s_addc_u32 s77, s77, 0
	global_load_dwordx4 v[218:221], v0, s[76:77]
	global_load_dwordx4 v[222:225], v0, s[76:77] offset:16
	global_load_dwordx4 v[226:229], v0, s[76:77] offset:32
	global_load_dwordx4 v[230:233], v0, s[76:77] offset:48
	s_add_u32 s76, s76, 0x6000
	s_addc_u32 s77, s77, 0
	global_load_dwordx4 v[234:237], v0, s[76:77]
	global_load_dwordx4 v[238:241], v0, s[76:77] offset:16
	global_load_dwordx4 v[242:245], v0, s[76:77] offset:32
	global_load_dwordx4 v[250:253], v0, s[76:77] offset:48
	s_add_u32 s76, s76, 0x6000
	s_addc_u32 s77, s77, 0
	global_load_dwordx4 v[108:111], v0, s[76:77]
	global_load_dwordx4 v[36:39], v0, s[76:77] offset:16
	global_load_dwordx4 v[40:43], v0, s[76:77] offset:32
	global_load_dwordx4 v[44:47], v0, s[76:77] offset:48
	s_waitcnt vmcnt(32)
	v_lshlrev_b32_e32 v20, 16, v12
	v_lshlrev_b32_e32 v21, 16, v13
	v_lshlrev_b32_e32 v22, 16, v14
	v_lshlrev_b32_e32 v23, 16, v15
	v_lshlrev_b32_e32 v24, 16, v16
	v_lshlrev_b32_e32 v25, 16, v17
	v_lshlrev_b32_e32 v26, 16, v18
	v_lshlrev_b32_e32 v27, 16, v19
	v_and_b32_e32 v12, 0xffff0000, v12
	v_and_b32_e32 v13, 0xffff0000, v13
	v_and_b32_e32 v14, 0xffff0000, v14
	v_and_b32_e32 v15, 0xffff0000, v15
	v_and_b32_e32 v16, 0xffff0000, v16
	v_and_b32_e32 v17, 0xffff0000, v17
	v_and_b32_e32 v18, 0xffff0000, v18
	v_and_b32_e32 v19, 0xffff0000, v19
	s_waitcnt vmcnt(28)
	v_mul_f32_e32 v102, v71, v12
	v_fmac_f32_e32 v102, v70, v20
	v_fmac_f32_e32 v102, v72, v21
	v_fmac_f32_e32 v102, v73, v13
	v_mul_f32_e32 v103, v75, v14
	v_fmac_f32_e32 v103, v74, v22
	v_fmac_f32_e32 v103, v76, v23
	v_fmac_f32_e32 v103, v77, v15
	v_mul_f32_e32 v130, v79, v16
	v_fmac_f32_e32 v130, v78, v24
	v_fmac_f32_e32 v130, v80, v25
	v_fmac_f32_e32 v130, v81, v17
	v_mul_f32_e32 v131, v83, v18
	v_fmac_f32_e32 v131, v82, v26
	v_fmac_f32_e32 v131, v84, v27
	v_fmac_f32_e32 v131, v85, v19
	v_add_f32_e32 v28, 0, v102
	v_add_f32_e32 v28, v28, v103
	v_add_f32_e32 v28, v28, v130
	v_add_f32_e32 v28, v28, v131
	s_waitcnt vmcnt(24)
	v_mul_f32_e32 v102, v87, v12
	v_fmac_f32_e32 v102, v86, v20
	v_fmac_f32_e32 v102, v88, v21
	v_fmac_f32_e32 v102, v89, v13
	v_mul_f32_e32 v103, v91, v14
	v_fmac_f32_e32 v103, v90, v22
	v_fmac_f32_e32 v103, v92, v23
	v_fmac_f32_e32 v103, v93, v15
	v_mul_f32_e32 v130, v95, v16
	v_fmac_f32_e32 v130, v94, v24
	v_fmac_f32_e32 v130, v96, v25
	v_fmac_f32_e32 v130, v97, v17
	v_mul_f32_e32 v131, v99, v18
	v_fmac_f32_e32 v131, v98, v26
	v_fmac_f32_e32 v131, v100, v27
	v_fmac_f32_e32 v131, v101, v19
	v_add_f32_e32 v29, 0, v102
	v_add_f32_e32 v29, v29, v103
	v_add_f32_e32 v29, v29, v130
	v_add_f32_e32 v29, v29, v131
	s_waitcnt vmcnt(20)
	v_mul_f32_e32 v102, v115, v12
	v_fmac_f32_e32 v102, v114, v20
	v_fmac_f32_e32 v102, v116, v21
	v_fmac_f32_e32 v102, v117, v13
	v_mul_f32_e32 v103, v119, v14
	v_fmac_f32_e32 v103, v118, v22
	v_fmac_f32_e32 v103, v120, v23
	v_fmac_f32_e32 v103, v121, v15
	v_mul_f32_e32 v130, v123, v16
	v_fmac_f32_e32 v130, v122, v24
	v_fmac_f32_e32 v130, v124, v25
	v_fmac_f32_e32 v130, v125, v17
	v_mul_f32_e32 v131, v127, v18
	v_fmac_f32_e32 v131, v126, v26
	v_fmac_f32_e32 v131, v128, v27
	v_fmac_f32_e32 v131, v129, v19
	v_add_f32_e32 v30, 0, v102
	v_add_f32_e32 v30, v30, v103
	v_add_f32_e32 v30, v30, v130
	v_add_f32_e32 v30, v30, v131
	s_waitcnt vmcnt(16)
	v_mul_f32_e32 v102, v181, v12
	v_fmac_f32_e32 v102, v180, v20
	v_fmac_f32_e32 v102, v182, v21
	v_fmac_f32_e32 v102, v183, v13
	v_mul_f32_e32 v103, v185, v14
	v_fmac_f32_e32 v103, v184, v22
	v_fmac_f32_e32 v103, v186, v23
	v_fmac_f32_e32 v103, v187, v15
	v_mul_f32_e32 v130, v189, v16
	v_fmac_f32_e32 v130, v188, v24
	v_fmac_f32_e32 v130, v190, v25
	v_fmac_f32_e32 v130, v191, v17
	v_mul_f32_e32 v131, v193, v18
	v_fmac_f32_e32 v131, v192, v26
	v_fmac_f32_e32 v131, v194, v27
	v_fmac_f32_e32 v131, v195, v19
	v_add_f32_e32 v31, 0, v102
	v_add_f32_e32 v31, v31, v103
	v_add_f32_e32 v31, v31, v130
	v_add_f32_e32 v31, v31, v131
	s_waitcnt vmcnt(12)
; __global__ void __launch_bounds__(512, 2) fwd_megakernel(Params p) {
;     ...
;             for (int b = 0; b < 8; ++b) { const f32x4* sp = (const f32x4*)(sh + b * 6144 + 16 * lane); float a = 0.f;
; #pragma unroll
;                 for (int j = 0; j < 4; ++j) { const f32x4 sv = sp[j]; a += sv[0] * wf[4 * j] + sv[1] * wf[4 * j + 1] + sv[2] * wf[4 * j + 2] + sv[3] * wf[4 * j + 3]; }
;                 a = wave_sum(a); if (lane == 0) dst[(size_t)b * ncol] = a; }
	v_mul_f32_e32 v102, v201, v12
	v_fmac_f32_e32 v102, v200, v20
	v_fmac_f32_e32 v102, v202, v21
	v_fmac_f32_e32 v102, v203, v13
	v_mul_f32_e32 v103, v207, v14
	v_fmac_f32_e32 v103, v206, v22
	v_fmac_f32_e32 v103, v208, v23
	v_fmac_f32_e32 v103, v209, v15
	v_mul_f32_e32 v130, v211, v16
	v_fmac_f32_e32 v130, v210, v24
	v_fmac_f32_e32 v130, v212, v25
	v_fmac_f32_e32 v130, v213, v17
	v_mul_f32_e32 v131, v215, v18
	v_fmac_f32_e32 v131, v214, v26
	v_fmac_f32_e32 v131, v216, v27
	v_fmac_f32_e32 v131, v217, v19
	v_add_f32_e32 v32, 0, v102
	v_add_f32_e32 v32, v32, v103
	v_add_f32_e32 v32, v32, v130
	v_add_f32_e32 v32, v32, v131
	s_waitcnt vmcnt(8)
	v_mul_f32_e32 v102, v219, v12
	v_fmac_f32_e32 v102, v218, v20
	v_fmac_f32_e32 v102, v220, v21
	v_fmac_f32_e32 v102, v221, v13
	v_mul_f32_e32 v103, v223, v14
	v_fmac_f32_e32 v103, v222, v22
	v_fmac_f32_e32 v103, v224, v23
	v_fmac_f32_e32 v103, v225, v15
	v_mul_f32_e32 v130, v227, v16
	v_fmac_f32_e32 v130, v226, v24
	v_fmac_f32_e32 v130, v228, v25
	v_fmac_f32_e32 v130, v229, v17
	v_mul_f32_e32 v131, v231, v18
	v_fmac_f32_e32 v131, v230, v26
	v_fmac_f32_e32 v131, v232, v27
	v_fmac_f32_e32 v131, v233, v19
	v_add_f32_e32 v33, 0, v102
	v_add_f32_e32 v33, v33, v103
	v_add_f32_e32 v33, v33, v130
	v_add_f32_e32 v33, v33, v131
	s_waitcnt vmcnt(4)
	v_mul_f32_e32 v102, v235, v12
	v_fmac_f32_e32 v102, v234, v20
	v_fmac_f32_e32 v102, v236, v21
	v_fmac_f32_e32 v102, v237, v13
	v_mul_f32_e32 v103, v239, v14
	v_fmac_f32_e32 v103, v238, v22
	v_fmac_f32_e32 v103, v240, v23
	v_fmac_f32_e32 v103, v241, v15
	v_mul_f32_e32 v130, v243, v16
	v_fmac_f32_e32 v130, v242, v24
	v_fmac_f32_e32 v130, v244, v25
	v_fmac_f32_e32 v130, v245, v17
	v_mul_f32_e32 v131, v251, v18
	v_fmac_f32_e32 v131, v250, v26
	v_fmac_f32_e32 v131, v252, v27
	v_fmac_f32_e32 v131, v253, v19
	v_add_f32_e32 v34, 0, v102
	v_add_f32_e32 v34, v34, v103
	v_add_f32_e32 v34, v34, v130
	v_add_f32_e32 v34, v34, v131
	s_waitcnt vmcnt(0)
	v_mul_f32_e32 v102, v109, v12
	v_fmac_f32_e32 v102, v108, v20
	v_fmac_f32_e32 v102, v110, v21
	v_fmac_f32_e32 v102, v111, v13
	v_mul_f32_e32 v103, v37, v14
	v_fmac_f32_e32 v103, v36, v22
	v_fmac_f32_e32 v103, v38, v23
	v_fmac_f32_e32 v103, v39, v15
	v_mul_f32_e32 v130, v41, v16
	v_fmac_f32_e32 v130, v40, v24
	v_fmac_f32_e32 v130, v42, v25
	v_fmac_f32_e32 v130, v43, v17
	v_mul_f32_e32 v131, v45, v18
	v_fmac_f32_e32 v131, v44, v26
	v_fmac_f32_e32 v131, v46, v27
	v_fmac_f32_e32 v131, v47, v19
	v_add_f32_e32 v35, 0, v102
	v_add_f32_e32 v35, v35, v103
	v_add_f32_e32 v35, v35, v130
	v_add_f32_e32 v35, v35, v131
	ds_bpermute_b32 v70, v4, v28
	ds_bpermute_b32 v71, v4, v29
	ds_bpermute_b32 v72, v4, v30
	ds_bpermute_b32 v73, v4, v31
	ds_bpermute_b32 v74, v4, v32
	ds_bpermute_b32 v75, v4, v33
	ds_bpermute_b32 v76, v4, v34
	ds_bpermute_b32 v77, v4, v35
	s_waitcnt lgkmcnt(0)
	v_add_f32_e32 v28, v28, v70
	v_add_f32_e32 v29, v29, v71
	v_add_f32_e32 v30, v30, v72
	v_add_f32_e32 v31, v31, v73
	v_add_f32_e32 v32, v32, v74
	v_add_f32_e32 v33, v33, v75
	v_add_f32_e32 v34, v34, v76
	v_add_f32_e32 v35, v35, v77
	ds_bpermute_b32 v70, v5, v28
	ds_bpermute_b32 v71, v5, v29
	ds_bpermute_b32 v72, v5, v30
	ds_bpermute_b32 v73, v5, v31
	ds_bpermute_b32 v74, v5, v32
	ds_bpermute_b32 v75, v5, v33
	ds_bpermute_b32 v76, v5, v34
	ds_bpermute_b32 v77, v5, v35
	s_waitcnt lgkmcnt(0)
	v_add_f32_e32 v28, v28, v70
	v_add_f32_e32 v29, v29, v71
	v_add_f32_e32 v30, v30, v72
	v_add_f32_e32 v31, v31, v73
	v_add_f32_e32 v32, v32, v74
	v_add_f32_e32 v33, v33, v75
	v_add_f32_e32 v34, v34, v76
	v_add_f32_e32 v35, v35, v77
	ds_bpermute_b32 v70, v6, v28
	ds_bpermute_b32 v71, v6, v29
	ds_bpermute_b32 v72, v6, v30
	ds_bpermute_b32 v73, v6, v31
	ds_bpermute_b32 v74, v6, v32
	ds_bpermute_b32 v75, v6, v33
	ds_bpermute_b32 v76, v6, v34
	ds_bpermute_b32 v77, v6, v35
	s_waitcnt lgkmcnt(0)
	v_add_f32_e32 v28, v28, v70
	v_add_f32_e32 v29, v29, v71
	v_add_f32_e32 v30, v30, v72
	v_add_f32_e32 v31, v31, v73
	v_add_f32_e32 v32, v32, v74
	v_add_f32_e32 v33, v33, v75
	v_add_f32_e32 v34, v34, v76
	v_add_f32_e32 v35, v35, v77
	ds_bpermute_b32 v70, v7, v28
	ds_bpermute_b32 v71, v7, v29
	ds_bpermute_b32 v72, v7, v30
	ds_bpermute_b32 v73, v7, v31
	ds_bpermute_b32 v74, v7, v32
	ds_bpermute_b32 v75, v7, v33
	ds_bpermute_b32 v76, v7, v34
	ds_bpermute_b32 v77, v7, v35
	s_waitcnt lgkmcnt(0)
	v_add_f32_e32 v28, v28, v70
	v_add_f32_e32 v29, v29, v71
	v_add_f32_e32 v30, v30, v72
	v_add_f32_e32 v31, v31, v73
	v_add_f32_e32 v32, v32, v74
	v_add_f32_e32 v33, v33, v75
	v_add_f32_e32 v34, v34, v76
	v_add_f32_e32 v35, v35, v77
	ds_bpermute_b32 v70, v8, v28
	ds_bpermute_b32 v71, v8, v29
	ds_bpermute_b32 v72, v8, v30
	ds_bpermute_b32 v73, v8, v31
	ds_bpermute_b32 v74, v8, v32
	ds_bpermute_b32 v75, v8, v33
	ds_bpermute_b32 v76, v8, v34
	ds_bpermute_b32 v77, v8, v35
	s_waitcnt lgkmcnt(0)
	v_add_f32_e32 v28, v28, v70
	v_add_f32_e32 v29, v29, v71
	v_add_f32_e32 v30, v30, v72
	v_add_f32_e32 v31, v31, v73
	v_add_f32_e32 v32, v32, v74
	v_add_f32_e32 v33, v33, v75
	v_add_f32_e32 v34, v34, v76
	v_add_f32_e32 v35, v35, v77
	ds_bpermute_b32 v70, v9, v28
	ds_bpermute_b32 v71, v9, v29
	ds_bpermute_b32 v72, v9, v30
	ds_bpermute_b32 v73, v9, v31
	ds_bpermute_b32 v74, v9, v32
	ds_bpermute_b32 v75, v9, v33
	ds_bpermute_b32 v76, v9, v34
	ds_bpermute_b32 v77, v9, v35
	s_waitcnt lgkmcnt(0)
	v_add_f32_e32 v28, v28, v70
	v_add_f32_e32 v29, v29, v71
	v_add_f32_e32 v30, v30, v72
	v_add_f32_e32 v31, v31, v73
	v_add_f32_e32 v32, v32, v74
	v_add_f32_e32 v33, v33, v75
	v_add_f32_e32 v34, v34, v76
	v_add_f32_e32 v35, v35, v77
	s_and_saveexec_b64 s[60:61], s[4:5]
	s_cbranch_execz .LBB0_180
	global_store_dword v1, v28, s[56:57]
	s_lshl_b32 s13, s58, 2
	v_mov_b32_e32 v102, s13
	global_store_dword v102, v29, s[56:57]
	v_add_u32_e32 v102, s13, v102
	global_store_dword v102, v30, s[56:57]
	v_add_u32_e32 v102, s13, v102
	global_store_dword v102, v31, s[56:57]
	v_add_u32_e32 v102, s13, v102
	global_store_dword v102, v32, s[56:57]
	v_add_u32_e32 v102, s13, v102
	global_store_dword v102, v33, s[56:57]
	v_add_u32_e32 v102, s13, v102
	global_store_dword v102, v34, s[56:57]
	v_add_u32_e32 v102, s13, v102
	global_store_dword v102, v35, s[56:57]
	s_branch .LBB0_180

; #define ATT_LOADK(t) do { kst[0] = *(const u32x4*)((const char*)KAp + (size_t)(t) * (size_t)(128 * ldka) + offA); \
;     if (HASB) { if (tid < 256) kst[KPT - 1] = *(const u32x4*)((const char*)KBp + (size_t)(t) * (size_t)(128 * ldkb) + offB); } } while (0)
; #define ATT_LOADV(t) do { _Pragma("unroll") for (int i = 0; i < VPT; ++i) vst[i] = *(const u32x4*)((const char*)Vp + ((size_t)(t) * 64 + (size_t)i * (512 / VCH)) * (size_t)(2 * ldv) + offV); } while (0)
; #define ATT_STOREK(sl) do { *(LAS u32x4*)(lds + (sl) * C::KBYTES + ldsA) = kst[0]; \
;     if (HASB) { if (tid < 256) *(LAS u32x4*)(lds + (sl) * C::KBYTES + ldsB) = kst[KPT - 1]; } } while (0)
; #define ATT_STOREV(sl) do { _Pragma("unroll") for (int i = 0; i < VPT; ++i) *(LAS u32x4*)(lds + C::VOFF + (sl) * C::VBYTES + i * (512 / VCH) * VP + ldsV) = vst[i]; } while (0)
; template <int DQK, int DKA, int DV> ...
;     ...
;     for (int t = 0; t < NT; ++t) {
;         const int ks1 = (t + 1) & 3;
;         if (t + 3 < NT) ATT_STOREK((t + 3) & 3);
;         if (t + 2 < NT) ATT_STOREV((t + 2) & 3);
;         if (t + 4 < NT) ATT_LOADK(t + 4);
;         if (t + 3 < NT) ATT_LOADV(t + 3);
;         if (64 * t <= qlast) {
.LBB0_1124:
	s_bitcmp1_b32 s1, 0
	s_cbranch_scc1 .Lslow_d
	s_add_i32 s23, s1, 1
	s_cmp_lt_u32 s23, s16
	s_cbranch_scc1 .Lfast_d

; template <int DQK, int DKA, int DV> ...
;     ...
;             } else if (__any(mx > RESC_THR)) {
;                 const float dl = fmaxf(mx, 0.f), alpha = __builtin_amdgcn_exp2f(-dl); m += dl;
;                 if (NEGM) {
; #pragma unroll
;                     for (int i = 0; i < 16; ++i) { p0[i] -= dl; p1[i] -= dl; }
; #pragma unroll
;                     for (int i = 0; i < 16; ++i) negm[i] = -m;
;                 }
;                 l *= alpha;
; #pragma unroll
;                 for (int v = 0; v < NV; ++v)
; #pragma unroll
;                     for (int i = 0; i < 16; ++i) o[v][i] *= alpha;
;             }
.Lorig_rare_d:
	v_max_f32_e32 v0, v232, v232
	v_max_f32_e32 v233, 0, v0
	v_exp_f32_e64 v232, -v233
	v_add_f32_e32 v230, v230, v233
	v_xor_b32_e32 v0, 0x80000000, v230
	v_mov_b32_e32 v1, v0
	v_mov_b32_e32 v2, v0
	v_mov_b32_e32 v3, v0
	v_mov_b32_e32 v4, v0
	v_mov_b32_e32 v5, v0
	v_mov_b32_e32 v6, v0
	v_mov_b32_e32 v7, v0
	v_mov_b32_e32 v8, v0
	v_mov_b32_e32 v9, v0
	v_mov_b32_e32 v10, v0
	v_mov_b32_e32 v11, v0
	v_mov_b32_e32 v12, v0
	v_mov_b32_e32 v13, v0
	v_mov_b32_e32 v14, v0
	v_mov_b32_e32 v15, v0
	v_sub_f32_e32 v96, v96, v233
	v_sub_f32_e32 v97, v97, v233
	v_sub_f32_e32 v98, v98, v233
	v_sub_f32_e32 v99, v99, v233
	v_sub_f32_e32 v100, v100, v233
	v_sub_f32_e32 v101, v101, v233
	v_sub_f32_e32 v102, v102, v233
	v_sub_f32_e32 v103, v103, v233
	v_sub_f32_e32 v104, v104, v233
	v_sub_f32_e32 v105, v105, v233
	v_sub_f32_e32 v106, v106, v233
	v_sub_f32_e32 v107, v107, v233
	v_sub_f32_e32 v108, v108, v233
	v_sub_f32_e32 v109, v109, v233
	v_sub_f32_e32 v110, v110, v233
	v_sub_f32_e32 v111, v111, v233
	v_pk_mul_f32 v[46:47], v[232:233], v[46:47] op_sel_hi:[0,1]
	v_pk_mul_f32 v[44:45], v[232:233], v[44:45] op_sel_hi:[0,1]
	v_pk_mul_f32 v[42:43], v[232:233], v[42:43] op_sel_hi:[0,1]
	v_pk_mul_f32 v[40:41], v[232:233], v[40:41] op_sel_hi:[0,1]
	v_pk_mul_f32 v[38:39], v[232:233], v[38:39] op_sel_hi:[0,1]
	v_pk_mul_f32 v[36:37], v[232:233], v[36:37] op_sel_hi:[0,1]
	v_pk_mul_f32 v[34:35], v[232:233], v[34:35] op_sel_hi:[0,1]
	v_pk_mul_f32 v[32:33], v[232:233], v[32:33] op_sel_hi:[0,1]
	v_pk_mul_f32 v[30:31], v[232:233], v[30:31] op_sel_hi:[0,1]
	v_pk_mul_f32 v[28:29], v[232:233], v[28:29] op_sel_hi:[0,1]
	v_pk_mul_f32 v[26:27], v[232:233], v[26:27] op_sel_hi:[0,1]
	v_pk_mul_f32 v[24:25], v[232:233], v[24:25] op_sel_hi:[0,1]
	v_pk_mul_f32 v[22:23], v[232:233], v[22:23] op_sel_hi:[0,1]
	v_pk_mul_f32 v[20:21], v[232:233], v[20:21] op_sel_hi:[0,1]
	v_pk_mul_f32 v[18:19], v[232:233], v[18:19] op_sel_hi:[0,1]
	v_pk_mul_f32 v[16:17], v[232:233], v[16:17] op_sel_hi:[0,1]
	v_pk_mul_f32 v[78:79], v[232:233], v[78:79] op_sel_hi:[0,1]
	v_pk_mul_f32 v[76:77], v[232:233], v[76:77] op_sel_hi:[0,1]
	v_pk_mul_f32 v[74:75], v[232:233], v[74:75] op_sel_hi:[0,1]
	v_pk_mul_f32 v[72:73], v[232:233], v[72:73] op_sel_hi:[0,1]
	v_pk_mul_f32 v[70:71], v[232:233], v[70:71] op_sel_hi:[0,1]
	v_pk_mul_f32 v[68:69], v[232:233], v[68:69] op_sel_hi:[0,1]
	v_pk_mul_f32 v[66:67], v[232:233], v[66:67] op_sel_hi:[0,1]
	v_pk_mul_f32 v[64:65], v[232:233], v[64:65] op_sel_hi:[0,1]
	v_pk_mul_f32 v[62:63], v[232:233], v[62:63] op_sel_hi:[0,1]
	v_pk_mul_f32 v[60:61], v[232:233], v[60:61] op_sel_hi:[0,1]
	v_pk_mul_f32 v[58:59], v[232:233], v[58:59] op_sel_hi:[0,1]
	v_pk_mul_f32 v[56:57], v[232:233], v[56:57] op_sel_hi:[0,1]
	v_pk_mul_f32 v[54:55], v[232:233], v[54:55] op_sel_hi:[0,1]
	v_pk_mul_f32 v[52:53], v[232:233], v[52:53] op_sel_hi:[0,1]
	v_pk_mul_f32 v[50:51], v[232:233], v[50:51] op_sel_hi:[0,1]
	v_pk_mul_f32 v[48:49], v[232:233], v[48:49] op_sel_hi:[0,1]
	v_sub_f32_e32 v80, v80, v233
	v_sub_f32_e32 v81, v81, v233
	v_sub_f32_e32 v82, v82, v233
	v_sub_f32_e32 v83, v83, v233
	v_sub_f32_e32 v84, v84, v233
	v_sub_f32_e32 v85, v85, v233
	v_sub_f32_e32 v86, v86, v233
	v_sub_f32_e32 v87, v87, v233
	v_sub_f32_e32 v88, v88, v233
	v_sub_f32_e32 v89, v89, v233
	v_sub_f32_e32 v90, v90, v233
	v_sub_f32_e32 v91, v91, v233
	v_sub_f32_e32 v92, v92, v233
	v_sub_f32_e32 v93, v93, v233
	v_sub_f32_e32 v94, v94, v233
	v_sub_f32_e32 v95, v95, v233
	v_mul_f32_e32 v231, v231, v232

; #define ATT_KFRAG(slot) do { LAS const unsigned char* kb_ = lds + (slot) * C::KBYTES + koff; \
;     _Pragma("unroll") for (int d0 = 0; d0 < ND; ++d0) { kf[2 * d0] = *(LAS const bf16x8*)(kb_ + 32 * d0); kf[2 * d0 + 1] = *(LAS const bf16x8*)(kb_ + 32 * KP + 32 * d0); } } while (0)
; #define ATT_VFRAG(vv) do { _Pragma("unroll") for (int j = 0; j < 2; ++j) _Pragma("unroll") for (int s4 = 0; s4 < 4; ++s4) { \
;         vlo[j * 4 + s4] = vtr(vb + (16 * s4) * VP + 64 * ((vv) + j)); vhi[j * 4 + s4] = vtr(vb + (16 * s4 + 8) * VP + 64 * ((vv) + j)); } } while (0)
; #define ATT_PV(vv) do { _Pragma("unroll") for (int s4 = 0; s4 < 4; ++s4) _Pragma("unroll") for (int j = 0; j < 2; ++j) { \
;         const bf16x8 vf = __builtin_shufflevector(vlo[j * 4 + s4], vhi[j * 4 + s4], 0, 1, 2, 3, 4, 5, 6, 7); o[(vv) + j] = MFMA32(vf, pf[s4], o[(vv) + j]); } } while (0)
; template <int DQK, int DKA, int DV> ...
;     ...
;                 __builtin_amdgcn_s_setprio(3); ATT_PV(0); __builtin_amdgcn_s_setprio(0);
;                 __builtin_amdgcn_sched_barrier(0);
;                 ATT_VFRAG(2);
;                 __builtin_amdgcn_sched_barrier(0);
;                 __builtin_amdgcn_s_setprio(3); ATT_PV(2); __builtin_amdgcn_s_setprio(0);
;                 __builtin_amdgcn_sched_barrier(0);
;                 if (t + 1 < NT) ATT_KFRAG(ks1);
.Lorig_pv_d:
	s_setprio 3
	s_waitcnt lgkmcnt(14)
	v_mfma_f32_32x32x16_bf16 v[32:47], v[196:199], v[232:235], v[32:47]
	s_waitcnt lgkmcnt(12)
	v_mfma_f32_32x32x16_bf16 v[16:31], v[200:203], v[232:235], v[16:31]
	s_waitcnt lgkmcnt(10)
	v_mfma_f32_32x32x16_bf16 v[32:47], v[192:195], v[240:243], v[32:47]
	s_waitcnt lgkmcnt(8)
	v_mfma_f32_32x32x16_bf16 v[16:31], v[188:191], v[240:243], v[16:31]
	s_waitcnt lgkmcnt(6)
	v_mfma_f32_32x32x16_bf16 v[32:47], v[184:187], v[236:239], v[32:47]
	s_waitcnt lgkmcnt(4)
	v_mfma_f32_32x32x16_bf16 v[16:31], v[180:183], v[236:239], v[16:31]
	s_waitcnt lgkmcnt(2)
	v_mfma_f32_32x32x16_bf16 v[32:47], v[176:179], v[244:247], v[32:47]
	s_waitcnt lgkmcnt(0)
	v_mfma_f32_32x32x16_bf16 v[16:31], v[172:175], v[244:247], v[16:31]
	s_setprio 0
	ds_read_b64_tr_b16 v[172:173], v210 offset:36992
	ds_read_b64_tr_b16 v[174:175], v210 offset:39552
	ds_read_b64_tr_b16 v[178:179], v210 offset:39616
	ds_read_b64_tr_b16 v[176:177], v210 offset:37056
	ds_read_b64_tr_b16 v[180:181], v210 offset:42112
	ds_read_b64_tr_b16 v[182:183], v210 offset:44672
	ds_read_b64_tr_b16 v[186:187], v210 offset:44736
	ds_read_b64_tr_b16 v[184:185], v210 offset:42176
	ds_read_b64_tr_b16 v[188:189], v210 offset:47232
	ds_read_b64_tr_b16 v[190:191], v210 offset:49792
	ds_read_b64_tr_b16 v[194:195], v210 offset:49856
	ds_read_b64_tr_b16 v[192:193], v210 offset:47296
	ds_read_b64_tr_b16 v[196:197], v210 offset:52352
	ds_read_b64_tr_b16 v[198:199], v210 offset:54912
	ds_read_b64_tr_b16 v[202:203], v210 offset:54976
	ds_read_b64_tr_b16 v[200:201], v210 offset:52416
	s_setprio 3
	s_waitcnt lgkmcnt(14)
	v_mfma_f32_32x32x16_bf16 v[64:79], v[172:175], v[232:235], v[64:79]
	s_waitcnt lgkmcnt(12)
	v_mfma_f32_32x32x16_bf16 v[48:63], v[176:179], v[232:235], v[48:63]
	s_waitcnt lgkmcnt(10)
	v_mfma_f32_32x32x16_bf16 v[64:79], v[180:183], v[240:243], v[64:79]
	s_waitcnt lgkmcnt(8)
	v_mfma_f32_32x32x16_bf16 v[48:63], v[184:187], v[240:243], v[48:63]
	s_waitcnt lgkmcnt(6)
	v_mfma_f32_32x32x16_bf16 v[64:79], v[188:191], v[236:239], v[64:79]
	s_waitcnt lgkmcnt(4)
	v_mfma_f32_32x32x16_bf16 v[48:63], v[192:195], v[236:239], v[48:63]
	s_waitcnt lgkmcnt(2)
	v_mfma_f32_32x32x16_bf16 v[64:79], v[196:199], v[244:247], v[64:79]
	s_waitcnt lgkmcnt(0)
	v_mfma_f32_32x32x16_bf16 v[48:63], v[200:203], v[244:247], v[48:63]
	s_setprio 0
	s_cmp_ge_u32 s51, s16
	s_cbranch_scc1 .LBB0_1140
	s_and_b32 s22, s51, 3
	s_mulk_i32 s22, 0x2400
	v_add_u32_e32 v164, s22, v226
	ds_read_b128 v[144:147], v164
	ds_read_b128 v[140:143], v164 offset:32
	ds_read_b128 v[152:155], v164 offset:4608
	ds_read_b128 v[148:151], v164 offset:4640
	ds_read_b128 v[156:159], v164 offset:64
	ds_read_b128 v[160:163], v164 offset:96
	ds_read_b128 v[168:171], v164 offset:4672
	ds_read_b128 v[164:167], v164 offset:4704

; #define LAS __attribute__((address_space(3)))
; template <int DQK, int DKA, int DV> ...
;     ...
;         if (t + 3 < NT) ATT_STOREK((t + 3) & 3);
;         if (t + 2 < NT) ATT_STOREV((t + 2) & 3);
;         if (t + 4 < NT) ATT_LOADK(t + 4);
;         if (t + 3 < NT) ATT_LOADV(t + 3);
;         if (64 * t <= qlast) {
;             f32x16 p0, p1; s16x4 vlo[8], vhi[8]; bf16x8 pf[4];
;             LAS const unsigned char* vb = lds + C::VOFF + (t & 3) * C::VBYTES + voff;
;             __builtin_amdgcn_sched_barrier(0);
;             __builtin_amdgcn_s_setprio(3);
; #pragma unroll
;             for (int d0 = 0; d0 < ND; ++d0) {
;                 if (d0 == 0) { p0 = MFMA32(kf[0], qr[0], negm); p1 = MFMA32(kf[1], qr[0], negm); }
;                 else { p0 = MFMA32(kf[2 * d0], qr[d0], p0); p1 = MFMA32(kf[2 * d0 + 1], qr[d0], p1); }
;             }
;             __builtin_amdgcn_s_setprio(0);
;             __builtin_amdgcn_sched_barrier(0);
;             ATT_VFRAG(0);
;             __builtin_amdgcn_sched_barrier(0);
;             if (64 * t + 63 > q0 + 32 * wid) {
;                 const int kvb = 64 * t + 4 * hi;
; #pragma unroll
;                 for (int i = 0; i < 16; ++i) { const int kv = kvb + (i & 3) + 8 * (i >> 2); if (kv > qabs) p0[i] = -INFINITY; if (kv + 32 > qabs) p1[i] = -INFINITY; }
;             }
;             float mxa = MAX3F(p0[0], p0[1], p1[0]), mxb = MAX3F(p0[2], p0[3], p1[1]); mxa = MAX3F(mxa, p1[2], p1[3]);
; #pragma unroll
;             for (int i = 4; i < 16; i += 4) { mxa = MAX3F(mxa, p0[i], p0[i + 1]); mxb = MAX3F(mxb, p0[i + 2], p0[i + 3]); mxa = MAX3F(mxa, p1[i], p1[i + 1]); mxb = MAX3F(mxb, p1[i + 2], p1[i + 3]); }
;             float mx = fmaxf(mxa, mxb);
;             { auto rr = __builtin_amdgcn_permlane32_swap(__float_as_uint(mx), __float_as_uint(mx), false, false); mx = fmaxf(__uint_as_float(rr[0]), __uint_as_float(rr[1])); }
;             if (!NEGM) mx -= m;
;             if (t == 0) {
;                 m = mx;
;                 if (NEGM) {
; #pragma unroll
;                     for (int i = 0; i < 16; ++i) { p0[i] -= mx; p1[i] -= mx; }
; #pragma unroll
;                     for (int i = 0; i < 16; ++i) negm[i] = -m;
;                 }
;             } else if (__any(mx > RESC_THR)) {
;                 const float dl = fmaxf(mx, 0.f), alpha = __builtin_amdgcn_exp2f(-dl); m += dl;
;                 if (NEGM) {
; #pragma unroll
.Lfast_d:
	s_add_i32 s80, s1, -1
	s_add_i32 s23, s1, -2
	s_and_b32 s22, s80, 3
	s_mulk_i32 s22, 0x2400
	v_add_u32_e32 v80, s22, v217
	s_waitcnt vmcnt(0)
	ds_write_b128 v80, v[128:131]
	s_and_b32 s22, s23, 3
	s_mulk_i32 s22, 0x5000
	v_add_u32_e32 v80, s22, v227
	ds_write_b128 v80, v[132:135] offset:36864
	ds_write_b128 v80, v[136:139] offset:47104
	global_load_dwordx4 v[128:131], v[218:219], off
	v_add_co_u32_e32 v80, vcc, 0x2000, v220
	s_nop 1
	v_addc_co_u32_e32 v81, vcc, 0, v221, vcc
	global_load_dwordx4 v[132:135], v[220:221], off
	global_load_dwordx4 v[136:139], v[80:81], off
	s_add_i32 s50, s1, -4
	s_and_b32 s22, s50, 3
	s_mulk_i32 s22, 0x5000
	v_add_u32_e32 v210, s22, v229
	s_add_i32 s51, s1, -3
	s_and_b32 s22, s51, 3
	s_mul_i32 s23, s22, 0x5000
	s_mulk_i32 s22, 0x2400
	v_add_u32_e32 v249, s22, v226
	v_add_u32_e32 v252, s23, v229
	s_setprio 3
	v_mfma_f32_32x32x16_bf16 v[80:95], v[144:147], v[112:115], v[0:15]
	ds_read_b128 v[144:147], v249
	v_mfma_f32_32x32x16_bf16 v[96:111], v[152:155], v[112:115], v[0:15]
	ds_read_b128 v[152:155], v249 offset:4608
	v_mfma_f32_32x32x16_bf16 v[80:95], v[140:143], v[116:119], v[80:95]
	ds_read_b128 v[140:143], v249 offset:32
	v_mfma_f32_32x32x16_bf16 v[96:111], v[148:151], v[116:119], v[96:111]
	ds_read_b128 v[148:151], v249 offset:4640
	v_mfma_f32_32x32x16_bf16 v[80:95], v[156:159], v[120:123], v[80:95]
	ds_read_b128 v[156:159], v249 offset:64
	v_mfma_f32_32x32x16_bf16 v[96:111], v[168:171], v[120:123], v[96:111]
	ds_read_b128 v[168:171], v249 offset:4672
	v_mfma_f32_32x32x16_bf16 v[80:95], v[160:163], v[124:127], v[80:95]
	ds_read_b128 v[160:163], v249 offset:96
	v_mfma_f32_32x32x16_bf16 v[96:111], v[164:167], v[124:127], v[96:111]
	ds_read_b128 v[164:167], v249 offset:4704
	s_setprio 0
	s_nop 7
	s_nop 4
	v_max_f32_e32 v232, v81, v81
	v_max_f32_e32 v233, v80, v80
	v_max_f32_e32 v232, v233, v232
	v_max3_f32 v233, v82, v83, v97
	v_max3_f32 v232, v232, v96, v98
	v_max3_f32 v232, v232, v99, v84
	v_max3_f32 v233, v233, v86, v87
	v_max3_f32 v232, v232, v85, v100
	v_max3_f32 v233, v233, v102, v103
	v_max3_f32 v232, v232, v101, v88
	v_max3_f32 v233, v233, v90, v91
	v_max3_f32 v232, v232, v89, v104
	v_max3_f32 v233, v233, v106, v107
	v_max3_f32 v232, v232, v105, v92
	v_max3_f32 v233, v233, v94, v95
	v_max3_f32 v232, v232, v93, v108
	v_max3_f32 v233, v233, v110, v111
	v_max3_f32 v232, v232, v109, v233
	v_mov_b32_e32 v233, v232
	s_nop 1
	v_permlane32_swap_b32_e32 v232, v233
	v_max_f32_e32 v233, v233, v233
	v_max_f32_e32 v232, v232, v232
	v_max_f32_e32 v232, v232, v233
	v_cmp_lt_f32_e32 vcc, s62, v232
	s_cbranch_vccnz .Lfast_d_bail1
	s_waitcnt lgkmcnt(0)
	v_exp_f32_e32 v80, v80
	v_exp_f32_e32 v96, v96
	v_exp_f32_e32 v81, v81
	v_exp_f32_e32 v97, v97
	v_mfma_f32_32x32x16_bf16 v[172:187], v[144:147], v[112:115], v[0:15]
	ds_read_b64_tr_b16 v[144:145], v210 offset:36864
	ds_read_b64_tr_b16 v[146:147], v210 offset:39424
	v_exp_f32_e32 v82, v82
	v_exp_f32_e32 v98, v98
	v_exp_f32_e32 v83, v83
	v_exp_f32_e32 v99, v99
	v_mfma_f32_32x32x16_bf16 v[188:203], v[152:155], v[112:115], v[0:15]
	ds_read_b64_tr_b16 v[152:153], v210 offset:36928
	ds_read_b64_tr_b16 v[154:155], v210 offset:39488
	v_exp_f32_e32 v84, v84
	v_exp_f32_e32 v100, v100
	v_exp_f32_e32 v85, v85
	v_exp_f32_e32 v101, v101
	v_mfma_f32_32x32x16_bf16 v[172:187], v[140:143], v[116:119], v[172:187]
	ds_read_b64_tr_b16 v[140:141], v210 offset:41984
	ds_read_b64_tr_b16 v[142:143], v210 offset:44544
	v_exp_f32_e32 v86, v86
	v_exp_f32_e32 v102, v102
	v_exp_f32_e32 v87, v87
	v_exp_f32_e32 v103, v103
	v_mfma_f32_32x32x16_bf16 v[188:203], v[148:151], v[116:119], v[188:203]
	ds_read_b64_tr_b16 v[148:149], v210 offset:42048
	ds_read_b64_tr_b16 v[150:151], v210 offset:44608
	v_exp_f32_e32 v88, v88
	v_exp_f32_e32 v104, v104
	v_exp_f32_e32 v89, v89
	v_exp_f32_e32 v105, v105
	v_mfma_f32_32x32x16_bf16 v[172:187], v[156:159], v[120:123], v[172:187]
	ds_read_b64_tr_b16 v[156:157], v210 offset:47104
	ds_read_b64_tr_b16 v[158:159], v210 offset:49664
	v_exp_f32_e32 v90, v90
	v_exp_f32_e32 v106, v106
	v_exp_f32_e32 v91, v91
	v_exp_f32_e32 v107, v107
	v_mfma_f32_32x32x16_bf16 v[188:203], v[168:171], v[120:123], v[188:203]
	ds_read_b64_tr_b16 v[168:169], v210 offset:47168
	ds_read_b64_tr_b16 v[170:171], v210 offset:49728
	v_exp_f32_e32 v92, v92
	v_exp_f32_e32 v108, v108
	v_exp_f32_e32 v93, v93
	v_exp_f32_e32 v109, v109
	v_mfma_f32_32x32x16_bf16 v[172:187], v[160:163], v[124:127], v[172:187]
	ds_read_b64_tr_b16 v[160:161], v210 offset:52224
	ds_read_b64_tr_b16 v[162:163], v210 offset:54784
	v_exp_f32_e32 v94, v94
	v_exp_f32_e32 v110, v110
	v_exp_f32_e32 v95, v95
	v_exp_f32_e32 v111, v111
	v_mfma_f32_32x32x16_bf16 v[188:203], v[164:167], v[124:127], v[188:203]
	ds_read_b64_tr_b16 v[164:165], v210 offset:52288
	ds_read_b64_tr_b16 v[166:167], v210 offset:54848
	v_cvt_pk_bf16_f32 v232, v80, v81
	v_cvt_pk_bf16_f32 v233, v82, v83
	v_cvt_pk_bf16_f32 v234, v84, v85
	v_cvt_pk_bf16_f32 v235, v86, v87
	v_cvt_pk_bf16_f32 v236, v96, v97
	v_cvt_pk_bf16_f32 v237, v98, v99
	v_cvt_pk_bf16_f32 v238, v100, v101
	v_cvt_pk_bf16_f32 v239, v102, v103
	v_cvt_pk_bf16_f32 v240, v88, v89
	v_cvt_pk_bf16_f32 v241, v90, v91
	v_cvt_pk_bf16_f32 v242, v92, v93
	v_cvt_pk_bf16_f32 v243, v94, v95
	v_cvt_pk_bf16_f32 v244, v104, v105
	v_cvt_pk_bf16_f32 v245, v106, v107
	v_cvt_pk_bf16_f32 v246, v108, v109
	v_cvt_pk_bf16_f32 v247, v110, v111
	v_max_f32_e32 v250, v173, v173
	v_max_f32_e32 v251, v172, v172
	v_max_f32_e32 v250, v251, v250
	v_max3_f32 v251, v174, v175, v189
	v_max3_f32 v250, v250, v188, v190
	v_max3_f32 v250, v250, v191, v176
	v_max3_f32 v251, v251, v178, v179
	v_max3_f32 v250, v250, v177, v192
	v_max3_f32 v251, v251, v194, v195
	v_max3_f32 v250, v250, v193, v180
	v_max3_f32 v251, v251, v182, v183
	v_max3_f32 v250, v250, v181, v196
	v_max3_f32 v251, v251, v198, v199
	v_max3_f32 v250, v250, v197, v184
	v_max3_f32 v251, v251, v186, v187
	v_max3_f32 v250, v250, v185, v200
	v_max3_f32 v251, v251, v202, v203
	v_max3_f32 v250, v250, v201, v251
	v_mov_b32_e32 v251, v250
	s_nop 1
	v_permlane32_swap_b32_e32 v250, v251
	v_max_f32_e32 v251, v251, v251
	v_max_f32_e32 v250, v250, v250
	v_max_f32_e32 v250, v250, v251
	v_cmp_lt_f32_e32 vcc, s62, v250
	s_cbranch_vccnz .Lfast_d_bail2
; __device__ __forceinline__ unsigned cvtpk_s(float lo, float hi) { f32x2_t v = {lo, hi}; bf16x2_t b = __builtin_convertvector(v, bf16x2_t); return __builtin_bit_cast(unsigned, b); }
; #define ATT_LOADK(t) do { kst[0] = *(const u32x4*)((const char*)KAp + (size_t)(t) * (size_t)(128 * ldka) + offA); \
;     if (HASB) { if (tid < 256) kst[KPT - 1] = *(const u32x4*)((const char*)KBp + (size_t)(t) * (size_t)(128 * ldkb) + offB); } } while (0)
; template <int DQK, int DKA, int DV> ...
;     ...
;         if (t + 3 < NT) ATT_STOREK((t + 3) & 3);
;         if (t + 2 < NT) ATT_STOREV((t + 2) & 3);
;         if (t + 4 < NT) ATT_LOADK(t + 4);
;         if (t + 3 < NT) ATT_LOADV(t + 3);
;     ...
;             { float rs = 0.f;
; #pragma unroll
;               for (int i = 0; i < 16; ++i) { p0[i] = __builtin_amdgcn_exp2f(NEGM ? p0[i] : p0[i] - m); p1[i] = __builtin_amdgcn_exp2f(NEGM ? p1[i] : p1[i] - m); rs += p0[i] + p1[i]; }
;               l += rs;
; #pragma unroll
;               for (int s = 0; s < 2; ++s) { u32x4 w0, w1;
;                 w0.x = cvtpk_s(p0[8 * s], p0[8 * s + 1]); w0.y = cvtpk_s(p0[8 * s + 2], p0[8 * s + 3]); w0.z = cvtpk_s(p0[8 * s + 4], p0[8 * s + 5]); w0.w = cvtpk_s(p0[8 * s + 6], p0[8 * s + 7]);
;                 w1.x = cvtpk_s(p1[8 * s], p1[8 * s + 1]); w1.y = cvtpk_s(p1[8 * s + 2], p1[8 * s + 3]); w1.z = cvtpk_s(p1[8 * s + 4], p1[8 * s + 5]); w1.w = cvtpk_s(p1[8 * s + 6], p1[8 * s + 7]);
;                 pf[s] = __builtin_bit_cast(bf16x8, w0); pf[2 + s] = __builtin_bit_cast(bf16x8, w1); } }
;             __builtin_amdgcn_sched_barrier(0);
;             if (NV == 2) {
;                 __builtin_amdgcn_s_setprio(3); ATT_PV(0); __builtin_amdgcn_s_setprio(0);
;                 __builtin_amdgcn_sched_barrier(0);
;                 if (t + 1 < NT) ATT_KFRAG(ks1);
;             } else {
;                 __builtin_amdgcn_s_setprio(3); ATT_PV(0); __builtin_amdgcn_s_setprio(0);
;                 __builtin_amdgcn_sched_barrier(0);
;                 ATT_VFRAG(2);
;                 __builtin_amdgcn_sched_barrier(0);
;                 __builtin_amdgcn_s_setprio(3); ATT_PV(2); __builtin_amdgcn_s_setprio(0);
;                 __builtin_amdgcn_sched_barrier(0);
;                 if (t + 1 < NT) ATT_KFRAG(ks1);
	s_setprio 0
	s_waitcnt lgkmcnt(0)
	v_mfma_f32_32x32x16_bf16 v[32:47], v[144:147], v[232:235], v[32:47]
	v_lshl_add_u64 v[218:219], v[218:219], 0, s[10:11]
	v_lshl_add_u64 v[220:221], v[220:221], 0, s[8:9]
	s_add_i32 s23, s1, -1
	s_and_b32 s22, s1, 3
	s_mulk_i32 s22, 0x2400
	v_add_u32_e32 v253, s22, v217
	s_waitcnt vmcnt(0)
	ds_write_b128 v253, v[128:131]
	s_and_b32 s22, s23, 3
	s_mulk_i32 s22, 0x5000
	v_mfma_f32_32x32x16_bf16 v[16:31], v[152:155], v[232:235], v[16:31]
	v_add_u32_e32 v253, s22, v227
	ds_write_b128 v253, v[132:135] offset:36864
	ds_write_b128 v253, v[136:139] offset:47104
	global_load_dwordx4 v[128:131], v[218:219], off
	v_add_co_u32_e32 v254, vcc, 0x2000, v220
	s_nop 1
	v_addc_co_u32_e32 v255, vcc, 0, v221, vcc
	global_load_dwordx4 v[132:135], v[220:221], off
	global_load_dwordx4 v[136:139], v[254:255], off
	v_add_f32_e32 v80, v80, v96
	v_add_f32_e32 v81, v81, v97
	v_add_f32_e32 v80, 0, v80
	v_add_f32_e32 v82, v82, v98
	v_mfma_f32_32x32x16_bf16 v[32:47], v[140:143], v[240:243], v[32:47]
	v_add_f32_e32 v80, v81, v80
	v_add_f32_e32 v83, v83, v99
	v_add_f32_e32 v80, v82, v80
	v_add_f32_e32 v84, v84, v100
	v_add_f32_e32 v80, v83, v80
	v_add_f32_e32 v85, v85, v101
	v_add_f32_e32 v80, v84, v80
	v_add_f32_e32 v86, v86, v102
	v_add_f32_e32 v80, v85, v80
	v_add_f32_e32 v87, v87, v103
	v_mfma_f32_32x32x16_bf16 v[16:31], v[148:151], v[240:243], v[16:31]
	v_add_f32_e32 v80, v86, v80
	v_add_f32_e32 v88, v88, v104
	v_add_f32_e32 v80, v87, v80
	v_add_f32_e32 v89, v89, v105
	v_add_f32_e32 v80, v88, v80
	v_add_f32_e32 v90, v90, v106
	v_add_f32_e32 v80, v89, v80
	v_add_f32_e32 v91, v91, v107
	v_add_f32_e32 v80, v90, v80
	v_add_f32_e32 v92, v92, v108
	v_mfma_f32_32x32x16_bf16 v[32:47], v[156:159], v[236:239], v[32:47]
	v_add_f32_e32 v80, v91, v80
	v_add_f32_e32 v93, v93, v109
	v_add_f32_e32 v80, v92, v80
	v_add_f32_e32 v94, v94, v110
	v_add_f32_e32 v80, v93, v80
	v_add_f32_e32 v95, v95, v111
	v_add_f32_e32 v80, v94, v80
	v_add_f32_e32 v80, v95, v80
	v_add_f32_e32 v231, v231, v80
	ds_read_b64_tr_b16 v[80:81], v210 offset:36992
	ds_read_b64_tr_b16 v[82:83], v210 offset:39552
	ds_read_b64_tr_b16 v[84:85], v210 offset:37056
	ds_read_b64_tr_b16 v[86:87], v210 offset:39616
	v_mfma_f32_32x32x16_bf16 v[16:31], v[168:171], v[236:239], v[16:31]
	ds_read_b64_tr_b16 v[88:89], v210 offset:42112
	ds_read_b64_tr_b16 v[90:91], v210 offset:44672
	ds_read_b64_tr_b16 v[92:93], v210 offset:42176
	ds_read_b64_tr_b16 v[94:95], v210 offset:44736
	ds_read_b64_tr_b16 v[96:97], v210 offset:47232
	ds_read_b64_tr_b16 v[98:99], v210 offset:49792
	ds_read_b64_tr_b16 v[100:101], v210 offset:47296
	ds_read_b64_tr_b16 v[102:103], v210 offset:49856
	v_mfma_f32_32x32x16_bf16 v[32:47], v[160:163], v[244:247], v[32:47]
	ds_read_b64_tr_b16 v[104:105], v210 offset:52352
	ds_read_b64_tr_b16 v[106:107], v210 offset:54912
	ds_read_b64_tr_b16 v[108:109], v210 offset:52416
	ds_read_b64_tr_b16 v[110:111], v210 offset:54976
	v_exp_f32_e32 v172, v172
	v_exp_f32_e32 v188, v188
	v_mfma_f32_32x32x16_bf16 v[16:31], v[164:167], v[244:247], v[16:31]
	v_exp_f32_e32 v173, v173
	v_exp_f32_e32 v189, v189
	v_exp_f32_e32 v174, v174
	v_exp_f32_e32 v190, v190
	s_waitcnt lgkmcnt(14)
	v_mfma_f32_32x32x16_bf16 v[64:79], v[80:83], v[232:235], v[64:79]
	v_exp_f32_e32 v175, v175
	v_exp_f32_e32 v191, v191
	v_exp_f32_e32 v176, v176
	v_exp_f32_e32 v192, v192
	s_waitcnt lgkmcnt(12)
	v_mfma_f32_32x32x16_bf16 v[48:63], v[84:87], v[232:235], v[48:63]
	v_exp_f32_e32 v177, v177
	v_exp_f32_e32 v193, v193
	v_exp_f32_e32 v178, v178
	v_exp_f32_e32 v194, v194
	s_waitcnt lgkmcnt(10)
	v_mfma_f32_32x32x16_bf16 v[64:79], v[88:91], v[240:243], v[64:79]
	v_exp_f32_e32 v179, v179
	v_exp_f32_e32 v195, v195
	v_exp_f32_e32 v180, v180
	s_waitcnt lgkmcnt(8)
	v_mfma_f32_32x32x16_bf16 v[48:63], v[92:95], v[240:243], v[48:63]
	v_exp_f32_e32 v196, v196
	v_exp_f32_e32 v181, v181
	v_exp_f32_e32 v197, v197
	s_waitcnt lgkmcnt(6)
	v_mfma_f32_32x32x16_bf16 v[64:79], v[96:99], v[236:239], v[64:79]
	v_exp_f32_e32 v182, v182
	v_exp_f32_e32 v198, v198
	v_exp_f32_e32 v183, v183
	s_waitcnt lgkmcnt(4)
	v_mfma_f32_32x32x16_bf16 v[48:63], v[100:103], v[236:239], v[48:63]
	v_exp_f32_e32 v199, v199
	v_exp_f32_e32 v184, v184
	v_exp_f32_e32 v200, v200
	s_waitcnt lgkmcnt(2)
	v_mfma_f32_32x32x16_bf16 v[64:79], v[104:107], v[244:247], v[64:79]
	v_exp_f32_e32 v185, v185
	v_exp_f32_e32 v201, v201
	v_exp_f32_e32 v186, v186
	s_waitcnt lgkmcnt(0)
; __device__ __forceinline__ unsigned cvtpk_s(float lo, float hi) { f32x2_t v = {lo, hi}; bf16x2_t b = __builtin_convertvector(v, bf16x2_t); return __builtin_bit_cast(unsigned, b); }
; #define ATT_KFRAG(slot) do { LAS const unsigned char* kb_ = lds + (slot) * C::KBYTES + koff; \
;     _Pragma("unroll") for (int d0 = 0; d0 < ND; ++d0) { kf[2 * d0] = *(LAS const bf16x8*)(kb_ + 32 * d0); kf[2 * d0 + 1] = *(LAS const bf16x8*)(kb_ + 32 * KP + 32 * d0); } } while (0)
; template <int DQK, int DKA, int DV> ...
;     ...
;             { float rs = 0.f;
; #pragma unroll
;               for (int i = 0; i < 16; ++i) { p0[i] = __builtin_amdgcn_exp2f(NEGM ? p0[i] : p0[i] - m); p1[i] = __builtin_amdgcn_exp2f(NEGM ? p1[i] : p1[i] - m); rs += p0[i] + p1[i]; }
;               l += rs;
; #pragma unroll
;               for (int s = 0; s < 2; ++s) { u32x4 w0, w1;
;                 w0.x = cvtpk_s(p0[8 * s], p0[8 * s + 1]); w0.y = cvtpk_s(p0[8 * s + 2], p0[8 * s + 3]); w0.z = cvtpk_s(p0[8 * s + 4], p0[8 * s + 5]); w0.w = cvtpk_s(p0[8 * s + 6], p0[8 * s + 7]);
;                 w1.x = cvtpk_s(p1[8 * s], p1[8 * s + 1]); w1.y = cvtpk_s(p1[8 * s + 2], p1[8 * s + 3]); w1.z = cvtpk_s(p1[8 * s + 4], p1[8 * s + 5]); w1.w = cvtpk_s(p1[8 * s + 6], p1[8 * s + 7]);
;                 pf[s] = __builtin_bit_cast(bf16x8, w0); pf[2 + s] = __builtin_bit_cast(bf16x8, w1); } }
;             __builtin_amdgcn_sched_barrier(0);
;             if (NV == 2) {
;                 __builtin_amdgcn_s_setprio(3); ATT_PV(0); __builtin_amdgcn_s_setprio(0);
;                 __builtin_amdgcn_sched_barrier(0);
;                 if (t + 1 < NT) ATT_KFRAG(ks1);
;             } else {
;                 __builtin_amdgcn_s_setprio(3); ATT_PV(0); __builtin_amdgcn_s_setprio(0);
;                 __builtin_amdgcn_sched_barrier(0);
;                 ATT_VFRAG(2);
;                 __builtin_amdgcn_sched_barrier(0);
;                 __builtin_amdgcn_s_setprio(3); ATT_PV(2); __builtin_amdgcn_s_setprio(0);
;                 __builtin_amdgcn_sched_barrier(0);
;                 if (t + 1 < NT) ATT_KFRAG(ks1);
;             }
;             __builtin_amdgcn_sched_barrier(0);
;         }
;         if (t & 1) asm volatile("s_waitcnt lgkmcnt(0)\n\ts_barrier" ::: "memory");
	v_mfma_f32_32x32x16_bf16 v[48:63], v[108:111], v[244:247], v[48:63]
	v_exp_f32_e32 v202, v202
	v_exp_f32_e32 v187, v187
	v_exp_f32_e32 v203, v203
	s_setprio 0
	v_cvt_pk_bf16_f32 v232, v172, v173
	ds_read_b64_tr_b16 v[144:145], v252 offset:36864
	v_cvt_pk_bf16_f32 v233, v174, v175
	ds_read_b64_tr_b16 v[146:147], v252 offset:39424
	v_cvt_pk_bf16_f32 v234, v176, v177
	ds_read_b64_tr_b16 v[152:153], v252 offset:36928
	v_cvt_pk_bf16_f32 v235, v178, v179
	ds_read_b64_tr_b16 v[154:155], v252 offset:39488
	v_cvt_pk_bf16_f32 v236, v188, v189
	ds_read_b64_tr_b16 v[140:141], v252 offset:41984
	v_cvt_pk_bf16_f32 v237, v190, v191
	ds_read_b64_tr_b16 v[142:143], v252 offset:44544
	v_cvt_pk_bf16_f32 v238, v192, v193
	ds_read_b64_tr_b16 v[148:149], v252 offset:42048
	v_cvt_pk_bf16_f32 v239, v194, v195
	ds_read_b64_tr_b16 v[150:151], v252 offset:44608
	v_cvt_pk_bf16_f32 v240, v180, v181
	ds_read_b64_tr_b16 v[156:157], v252 offset:47104
	v_cvt_pk_bf16_f32 v241, v182, v183
	ds_read_b64_tr_b16 v[158:159], v252 offset:49664
	v_cvt_pk_bf16_f32 v242, v184, v185
	ds_read_b64_tr_b16 v[168:169], v252 offset:47168
	v_cvt_pk_bf16_f32 v243, v186, v187
	ds_read_b64_tr_b16 v[170:171], v252 offset:49728
	v_cvt_pk_bf16_f32 v244, v196, v197
	ds_read_b64_tr_b16 v[160:161], v252 offset:52224
	v_cvt_pk_bf16_f32 v245, v198, v199
	ds_read_b64_tr_b16 v[162:163], v252 offset:54784
	v_cvt_pk_bf16_f32 v246, v200, v201
	ds_read_b64_tr_b16 v[164:165], v252 offset:52288
	v_cvt_pk_bf16_f32 v247, v202, v203
	ds_read_b64_tr_b16 v[166:167], v252 offset:54848
	v_add_f32_e32 v172, v172, v188
	v_add_f32_e32 v173, v173, v189
	v_add_f32_e32 v172, 0, v172
	v_add_f32_e32 v174, v174, v190
	v_add_f32_e32 v172, v173, v172
	v_add_f32_e32 v175, v175, v191
	v_add_f32_e32 v172, v174, v172
	v_add_f32_e32 v176, v176, v192
	v_add_f32_e32 v172, v175, v172
	v_add_f32_e32 v177, v177, v193
	v_add_f32_e32 v172, v176, v172
	v_add_f32_e32 v178, v178, v194
	s_waitcnt lgkmcnt(0)
	v_mfma_f32_32x32x16_bf16 v[32:47], v[144:147], v[232:235], v[32:47]
	ds_read_b64_tr_b16 v[80:81], v252 offset:36992
	ds_read_b64_tr_b16 v[82:83], v252 offset:39552
	ds_read_b64_tr_b16 v[84:85], v252 offset:37056
	ds_read_b64_tr_b16 v[86:87], v252 offset:39616
	v_add_f32_e32 v172, v177, v172
	v_add_f32_e32 v179, v179, v195
	v_add_f32_e32 v172, v178, v172
	v_mfma_f32_32x32x16_bf16 v[16:31], v[152:155], v[232:235], v[16:31]
	ds_read_b64_tr_b16 v[88:89], v252 offset:42112
	ds_read_b64_tr_b16 v[90:91], v252 offset:44672
	ds_read_b64_tr_b16 v[92:93], v252 offset:42176
	ds_read_b64_tr_b16 v[94:95], v252 offset:44736
	v_add_f32_e32 v180, v180, v196
	v_add_f32_e32 v172, v179, v172
	v_add_f32_e32 v181, v181, v197
	v_mfma_f32_32x32x16_bf16 v[32:47], v[140:143], v[240:243], v[32:47]
	ds_read_b64_tr_b16 v[96:97], v252 offset:47232
	ds_read_b64_tr_b16 v[98:99], v252 offset:49792
	ds_read_b64_tr_b16 v[100:101], v252 offset:47296
	ds_read_b64_tr_b16 v[102:103], v252 offset:49856
	v_add_f32_e32 v172, v180, v172
	v_add_f32_e32 v182, v182, v198
	v_add_f32_e32 v172, v181, v172
	v_mfma_f32_32x32x16_bf16 v[16:31], v[148:151], v[240:243], v[16:31]
	ds_read_b64_tr_b16 v[104:105], v252 offset:52352
	ds_read_b64_tr_b16 v[106:107], v252 offset:54912
	ds_read_b64_tr_b16 v[108:109], v252 offset:52416
	ds_read_b64_tr_b16 v[110:111], v252 offset:54976
	v_add_f32_e32 v183, v183, v199
	v_add_f32_e32 v172, v182, v172
	v_add_f32_e32 v184, v184, v200
	v_mfma_f32_32x32x16_bf16 v[32:47], v[156:159], v[236:239], v[32:47]
	v_add_f32_e32 v172, v183, v172
	v_add_f32_e32 v185, v185, v201
	v_add_f32_e32 v172, v184, v172
	v_mfma_f32_32x32x16_bf16 v[16:31], v[168:171], v[236:239], v[16:31]
	v_add_f32_e32 v186, v186, v202
	v_add_f32_e32 v172, v185, v172
	v_add_f32_e32 v187, v187, v203
	v_mfma_f32_32x32x16_bf16 v[32:47], v[160:163], v[244:247], v[32:47]
	v_add_f32_e32 v172, v186, v172
	v_add_f32_e32 v172, v187, v172
	v_add_f32_e32 v231, v231, v172
	v_mfma_f32_32x32x16_bf16 v[16:31], v[164:167], v[244:247], v[16:31]
	s_add_i32 s1, s1, 2
	s_addk_i32 s79, 0x80
	s_add_i32 s22, s1, -4
	s_and_b32 s22, s22, 3
	s_mulk_i32 s22, 0x2400
	v_add_u32_e32 v249, s22, v226
	s_waitcnt lgkmcnt(0)
	v_mfma_f32_32x32x16_bf16 v[64:79], v[80:83], v[232:235], v[64:79]
	ds_read_b128 v[144:147], v249
	ds_read_b128 v[152:155], v249 offset:4608
	v_mfma_f32_32x32x16_bf16 v[48:63], v[84:87], v[232:235], v[48:63]
	ds_read_b128 v[140:143], v249 offset:32
	ds_read_b128 v[148:151], v249 offset:4640
	v_mfma_f32_32x32x16_bf16 v[64:79], v[88:91], v[240:243], v[64:79]
	ds_read_b128 v[156:159], v249 offset:64
	ds_read_b128 v[168:171], v249 offset:4672
	v_mfma_f32_32x32x16_bf16 v[48:63], v[92:95], v[240:243], v[48:63]
	ds_read_b128 v[160:163], v249 offset:96
	ds_read_b128 v[164:167], v249 offset:4704
	v_mfma_f32_32x32x16_bf16 v[64:79], v[96:99], v[236:239], v[64:79]
	v_lshl_add_u64 v[218:219], v[218:219], 0, s[10:11]
	v_mfma_f32_32x32x16_bf16 v[48:63], v[100:103], v[236:239], v[48:63]
	v_lshl_add_u64 v[220:221], v[220:221], 0, s[8:9]
	v_mfma_f32_32x32x16_bf16 v[64:79], v[104:107], v[244:247], v[64:79]
	v_mfma_f32_32x32x16_bf16 v[48:63], v[108:111], v[244:247], v[48:63]
	s_setprio 0
	s_waitcnt lgkmcnt(0)
	s_barrier
	s_branch .LBB0_1124
.Lfast_d_bail1:
	s_waitcnt lgkmcnt(0)
	ds_read_b64_tr_b16 v[196:197], v210 offset:36864
	ds_read_b64_tr_b16 v[198:199], v210 offset:39424
	ds_read_b64_tr_b16 v[202:203], v210 offset:39488
	ds_read_b64_tr_b16 v[200:201], v210 offset:36928
	ds_read_b64_tr_b16 v[192:193], v210 offset:41984
	ds_read_b64_tr_b16 v[194:195], v210 offset:44544
	ds_read_b64_tr_b16 v[190:191], v210 offset:44608
	ds_read_b64_tr_b16 v[188:189], v210 offset:42048
	ds_read_b64_tr_b16 v[184:185], v210 offset:47104
	ds_read_b64_tr_b16 v[186:187], v210 offset:49664
	ds_read_b64_tr_b16 v[182:183], v210 offset:49728
	ds_read_b64_tr_b16 v[180:181], v210 offset:47168
	ds_read_b64_tr_b16 v[176:177], v210 offset:52224
	ds_read_b64_tr_b16 v[178:179], v210 offset:54784
	ds_read_b64_tr_b16 v[174:175], v210 offset:54848
	ds_read_b64_tr_b16 v[172:173], v210 offset:52288
	s_branch .Lorig_rare_d

; __global__ void __launch_bounds__(512, 2) fwd_megakernel(Params p) {
	.amdhsa_kernel _Z14fwd_megakernel6Params
		.amdhsa_group_segment_fixed_size 0
		.amdhsa_private_segment_fixed_size 0
		.amdhsa_kernarg_size 480
		.amdhsa_user_sgpr_count 2
		.amdhsa_user_sgpr_dispatch_ptr 0
		.amdhsa_user_sgpr_queue_ptr 0
		.amdhsa_user_sgpr_kernarg_segment_ptr 1
		.amdhsa_user_sgpr_dispatch_id 0
		.amdhsa_user_sgpr_kernarg_preload_length 0
		.amdhsa_user_sgpr_kernarg_preload_offset 0
		.amdhsa_user_sgpr_private_segment_size 0
		.amdhsa_uses_dynamic_stack 0
		.amdhsa_enable_private_segment 0
		.amdhsa_system_sgpr_workgroup_id_x 1
		.amdhsa_system_sgpr_workgroup_id_y 0
		.amdhsa_system_sgpr_workgroup_id_z 0
		.amdhsa_system_sgpr_workgroup_info 0
		.amdhsa_system_vgpr_workitem_id 2
		.amdhsa_next_free_vgpr 256
		.amdhsa_next_free_sgpr 98
		.amdhsa_accum_offset 256
		.amdhsa_reserve_vcc 1
		.amdhsa_float_round_mode_32 0
		.amdhsa_float_round_mode_16_64 0
		.amdhsa_float_denorm_mode_32 3
		.amdhsa_float_denorm_mode_16_64 3
		.amdhsa_dx10_clamp 1
		.amdhsa_ieee_mode 1
		.amdhsa_fp16_overflow 0
		.amdhsa_tg_split 0
		.amdhsa_exception_fp_ieee_invalid_op 0
		.amdhsa_exception_fp_denorm_src 0
		.amdhsa_exception_fp_ieee_div_zero 0
		.amdhsa_exception_fp_ieee_overflow 0
		.amdhsa_exception_fp_ieee_underflow 0
		.amdhsa_exception_fp_ieee_inexact 0
		.amdhsa_exception_int_div_zero 0
	.end_amdhsa_kernel

; __global__ void __launch_bounds__(512, 2) fwd_megakernel(Params p) {
amdhsa.kernels:
  - .agpr_count:     0
    .args:
      - .offset:         0
        .size:           224
        .value_kind:     by_value
      - .offset:         224
        .size:           4
        .value_kind:     hidden_block_count_x
      - .offset:         228
        .size:           4
        .value_kind:     hidden_block_count_y
      - .offset:         232
        .size:           4
        .value_kind:     hidden_block_count_z
      - .offset:         236
        .size:           2
        .value_kind:     hidden_group_size_x
      - .offset:         238
        .size:           2
        .value_kind:     hidden_group_size_y
      - .offset:         240
        .size:           2
        .value_kind:     hidden_group_size_z
      - .offset:         242
        .size:           2
        .value_kind:     hidden_remainder_x
      - .offset:         244
        .size:           2
        .value_kind:     hidden_remainder_y
      - .offset:         246
        .size:           2
        .value_kind:     hidden_remainder_z
      - .offset:         264
        .size:           8
        .value_kind:     hidden_global_offset_x
      - .offset:         272
        .size:           8
        .value_kind:     hidden_global_offset_y
      - .offset:         280
        .size:           8
        .value_kind:     hidden_global_offset_z
      - .offset:         288
        .size:           2
        .value_kind:     hidden_grid_dims
      - .offset:         312
        .size:           8
        .value_kind:     hidden_multigrid_sync_arg
      - .offset:         344
        .size:           4
        .value_kind:     hidden_dynamic_lds_size
    .group_segment_fixed_size: 0
    .kernarg_segment_align: 8
    .kernarg_segment_size: 480
    .language:       OpenCL C
    .language_version:
      - 2
      - 0
    .max_flat_workgroup_size: 512
    .name:           _Z14fwd_megakernel6Params
    .private_segment_fixed_size: 0
    .sgpr_count:     104
    .sgpr_spill_count: 14
    .symbol:         _Z14fwd_megakernel6Params.kd
    .uniform_work_group_size: 1
    .uses_dynamic_stack: false
    .vgpr_count:     256
    .vgpr_spill_count: 0
    .wavefront_size: 64
